# P6a head loop: six first-half r/k/v loads issued at the top of the iteration (three direct, three via new staging registers v248..255/v240..243); no live register touched
# baseline (speedup 1.0000x reference)
; __device__ __forceinline__ void prep_rwkv_phase(const Params& p, LAS unsigned char* lds, int gw, int ngw, int wave, int lane) {
;     ...
;         if (active) {
;         {
;             f32x4 accG[4];
; #pragma unroll
;             for (int i = 0; i < 4; ++i) { accG[i] = (f32x4){0.f, 0.f, 0.f, 0.f};
; #pragma unroll
;                 for (int ks = 0; ks < 4; ++ks) {
;                     const bf16x8 wg = *(const LAS bf16x8*)(WG + (i * 16 + fr) * 136 + ks * 32 + fq * 8), ag = *(const LAS bf16x8*)(act + fr * 264 + 128 + ks * 32 + fq * 8);
;                     accG[i] = __builtin_amdgcn_mfma_f32_16x16x32_bf16(wg, ag, accG[i], 0, 0, 0); } }
; #pragma unroll
;             for (int hf = 0; hf < 2; ++hf)
;                 *(u32x4*)(G + (size_t)m * 512 + h * 64 + fq * 16 + hf * 8) = (u32x4){pk2(accG[2 * hf][0], accG[2 * hf][1]), pk2(accG[2 * hf][2], accG[2 * hf][3]), pk2(accG[2 * hf + 1][0], accG[2 * hf + 1][1]), pk2(accG[2 * hf + 1][2], accG[2 * hf + 1][3])};
;         }
;         f32x4 accD[4], accA[4];
; #pragma unroll
;         for (int i = 0; i < 4; ++i) {
;             accD[i] = (f32x4){0.f, 0.f, 0.f, 0.f}; accA[i] = accD[i];
; #pragma unroll
;             for (int ks = 0; ks < 2; ++ks) {
;                 const bf16x8 wd = *(const LAS bf16x8*)(WD + (i * 16 + fr) * 72 + ks * 32 + fq * 8), ad = *(const LAS bf16x8*)(act + fr * 264 + ks * 32 + fq * 8);
;                 accD[i] = __builtin_amdgcn_mfma_f32_16x16x32_bf16(wd, ad, accD[i], 0, 0, 0);
;                 const bf16x8 wa = *(const LAS bf16x8*)(WA + (i * 16 + fr) * 72 + ks * 32 + fq * 8), aa = *(const LAS bf16x8*)(act + fr * 264 + 64 + ks * 32 + fq * 8);
;                 accA[i] = __builtin_amdgcn_mfma_f32_16x16x32_bf16(wa, aa, accA[i], 0, 0, 0);
;             }
;         }
;         float nk = 0.f, sbr = 0.f, skr = 0.f, sbo = 0.f;
;         u32x4 kcs[2], kps[2];
; #pragma unroll
;         for (int hf = 0; hf < 2; ++hf) {
;             const int o_ = h * 64 + fq * 16 + hf * 8;
;             kcs[hf] = *(const u32x4*)(prow + 512 + o_); kps[hf] = *(const u32x4*)(pprev + 512 + o_); if (first) kps[hf] = (u32x4){0u, 0u, 0u, 0u};
;             const u32x4 kc = kcs[hf], kp = kps[hf];
; #pragma unroll
;             for (int i2 = 0; i2 < 2; ++i2) { const int c = h * 64 + (2 * hf + i2) * 16 + 4 * fq; const f32x4 muk = *(const LAS f32x4*)(PRM + 512 + c), kk4 = *(const LAS f32x4*)(PRM + 2560 + c);
; #pragma unroll
.LBB0_857:
	s_andn2_b64 vcc, exec, s[20:21]
	s_cbranch_vccnz .LBB0_861
	v_ashrrev_i32_e32 v145, 31, v144
	v_lshlrev_b64 v[0:1], 1, v[144:145]
	v_lshl_add_u64 v[154:155], v[136:137], 0, v[0:1]
	v_lshl_add_u64 v[152:153], v[134:135], 0, v[0:1]
	global_load_dwordx4 v[248:251], v[154:155], off offset:1024
	global_load_dwordx4 v[252:255], v[154:155], off offset:1040
	global_load_dwordx4 v[168:171], v[152:153], off offset:1040
	global_load_dwordx4 v[176:179], v[154:155], off offset:2048
	global_load_dwordx4 v[180:183], v[154:155], off
	global_load_dwordx4 v[240:243], v[152:153], off offset:2048
	s_waitcnt lgkmcnt(1)
	ds_read_b128 v[20:23], v222
	ds_read_b128 v[24:27], v213 offset:256
	ds_read_b128 v[28:31], v222 offset:64
	ds_read_b128 v[32:35], v213 offset:320
	ds_read_b128 v[36:39], v222 offset:4352
	ds_read_b128 v[40:43], v222 offset:4416
	ds_read_b128 v[44:47], v222 offset:128
	ds_read_b128 v[48:51], v222 offset:192
	s_waitcnt lgkmcnt(6)
	v_mfma_f32_16x16x32_bf16 v[20:23], v[20:23], v[24:27], 0
	v_lshl_add_u64 v[0:1], s[92:93], 0, v[142:143]
	v_add_co_u32_e32 v0, vcc, s28, v0
	s_waitcnt lgkmcnt(4)
	v_mfma_f32_16x16x32_bf16 v[20:23], v[28:31], v[32:35], v[20:23]
	ds_read_b128 v[28:31], v213 offset:384
	ds_read_b128 v[52:55], v213 offset:448
	v_addc_co_u32_e32 v1, vcc, 0, v1, vcc
	s_waitcnt lgkmcnt(5)
	v_mfma_f32_16x16x32_bf16 v[36:39], v[36:39], v[24:27], 0
	v_ashrrev_i32_e32 v145, 31, v144
	v_add_u32_e32 v187, s31, v97
	v_add_u32_e32 v2, 0x11040, v187
	s_waitcnt lgkmcnt(1)
	v_mfma_f32_16x16x32_bf16 v[20:23], v[44:47], v[28:31], v[20:23]
	ds_read_b128 v[44:47], v222 offset:4480
	v_mfma_f32_16x16x32_bf16 v[36:39], v[40:43], v[32:35], v[36:39]
	ds_read_b128 v[40:43], v222 offset:4544
	s_waitcnt lgkmcnt(1)
	v_mfma_f32_16x16x32_bf16 v[36:39], v[44:47], v[28:31], v[36:39]
	ds_read_b128 v[44:47], v222 offset:8704
	s_waitcnt lgkmcnt(1)
	v_mfma_f32_16x16x32_bf16 v[36:39], v[40:43], v[52:55], v[36:39]
	ds_read_b128 v[40:43], v222 offset:8768
	v_mfma_f32_16x16x32_bf16 v[20:23], v[48:51], v[52:55], v[20:23]
	ds_read_b128 v[48:51], v222 offset:8832
	s_waitcnt lgkmcnt(2)
	v_mfma_f32_16x16x32_bf16 v[44:47], v[44:47], v[24:27], 0
	s_waitcnt lgkmcnt(1)
	v_mfma_f32_16x16x32_bf16 v[40:43], v[40:43], v[32:35], v[44:47]
	s_nop 2
	v_cvt_pk_bf16_f32 v20, v20, v21
	v_cvt_pk_bf16_f32 v21, v22, v23
	v_cvt_pk_bf16_f32 v22, v36, v37
	ds_read_b128 v[44:47], v222 offset:8896
	s_waitcnt lgkmcnt(1)
	v_mfma_f32_16x16x32_bf16 v[40:43], v[48:51], v[28:31], v[40:43]
	ds_read_b128 v[48:51], v222 offset:13056
	ds_read_b128 v[56:59], v222 offset:13120
	v_cvt_pk_bf16_f32 v23, v38, v39
	s_waitcnt lgkmcnt(1)
	v_mfma_f32_16x16x32_bf16 v[24:27], v[48:51], v[24:27], 0
	v_mfma_f32_16x16x32_bf16 v[40:43], v[44:47], v[52:55], v[40:43]
	ds_read_b128 v[44:47], v222 offset:13184
	ds_read_b128 v[60:63], v222 offset:13248
	global_store_dwordx4 v[0:1], v[20:23], off
	s_waitcnt lgkmcnt(2)
	v_mfma_f32_16x16x32_bf16 v[24:27], v[56:59], v[32:35], v[24:27]
	s_nop 2
	v_cvt_pk_bf16_f32 v20, v40, v41
	v_cvt_pk_bf16_f32 v21, v42, v43
	s_waitcnt lgkmcnt(1)
	v_mfma_f32_16x16x32_bf16 v[24:27], v[44:47], v[28:31], v[24:27]
	s_waitcnt lgkmcnt(0)
	v_mfma_f32_16x16x32_bf16 v[22:25], v[60:63], v[52:55], v[24:27]
	s_nop 7
	v_cvt_pk_bf16_f32 v22, v22, v23
	v_cvt_pk_bf16_f32 v23, v24, v25
	global_store_dwordx4 v[0:1], v[20:23], off offset:16
	v_lshlrev_b64 v[0:1], 1, v[144:145]
	v_lshl_add_u64 v[154:155], v[136:137], 0, v[0:1]
	s_nop 1
	s_waitcnt vmcnt(7)
	v_mov_b64_e32 v[20:21], v[248:249]
	v_mov_b64_e32 v[22:23], v[250:251]
	global_load_dwordx4 v[248:251], v[154:155], off offset:16
	ds_read_b128 v[24:27], v214
	ds_read_b128 v[28:31], v213
	s_nop 1
	s_waitcnt vmcnt(7)
	v_mov_b64_e32 v[32:33], v[252:253]
	v_mov_b64_e32 v[34:35], v[254:255]
	global_load_dwordx4 v[252:255], v[154:155], off offset:2064
	ds_read_b128 v[36:39], v215
	ds_read_b128 v[78:81], v213 offset:128
	ds_read_b128 v[40:43], v214 offset:64
	ds_read_b128 v[82:85], v213 offset:64
	s_waitcnt lgkmcnt(4)
	v_mfma_f32_16x16x32_bf16 v[24:27], v[24:27], v[28:31], 0
	v_lshl_add_u64 v[152:153], v[134:135], 0, v[0:1]
	ds_read_b128 v[44:47], v215 offset:64
	ds_read_b128 v[156:159], v213 offset:192
	s_nop 1
	s_waitcnt vmcnt(7)
	s_waitcnt lgkmcnt(2)
	v_mfma_f32_16x16x32_bf16 v[90:93], v[40:43], v[82:85], v[24:27]
	v_add_u32_e32 v0, 0x11000, v187
	v_add_u32_e32 v1, 0x13000, v187
	s_nop 0
	v_cndmask_b32_e64 v228, v20, 0, s[6:7]
	ds_read_b128 v[24:27], v216
	v_mfma_f32_16x16x32_bf16 v[36:39], v[36:39], v[78:81], 0
	v_add_u32_e32 v20, 0x13080, v187
	v_cndmask_b32_e64 v130, v23, 0, s[6:7]
	v_cndmask_b32_e64 v151, v22, 0, s[6:7]
	s_waitcnt lgkmcnt(1)
	v_mfma_f32_16x16x32_bf16 v[86:89], v[44:47], v[156:159], v[36:39]
	s_nop 2
	ds_read_b128 v[36:39], v217
	ds_read_b128 v[40:43], v216 offset:64
	ds_read_b128 v[44:47], v217 offset:64
	ds_read_b128 v[54:57], v218
	ds_read_b128 v[58:61], v218 offset:64
	ds_read_b128 v[62:65], v219
	ds_read_b128 v[66:69], v219 offset:64
	ds_read_b128 v[160:163], v220
	ds_read_b128 v[164:167], v220 offset:64
	s_waitcnt lgkmcnt(9)
	v_mfma_f32_16x16x32_bf16 v[24:27], v[24:27], v[28:31], 0
	v_cndmask_b32_e64 v186, v21, 0, s[6:7]
	s_nop 0
	v_cndmask_b32_e64 v33, v33, 0, s[6:7]
	v_cndmask_b32_e64 v48, v35, 0, s[6:7]
	s_waitcnt lgkmcnt(7)
	v_mfma_f32_16x16x32_bf16 v[50:53], v[40:43], v[82:85], v[24:27]
	s_nop 2
	ds_read_b128 v[24:27], v221
	ds_read_b128 v[172:175], v221 offset:64
	s_nop 1
	s_waitcnt vmcnt(6)
	s_nop 1
	s_waitcnt vmcnt(5)
	v_mfma_f32_16x16x32_bf16 v[36:39], v[36:39], v[78:81], 0
	s_nop 0
	v_and_b32_e32 v132, 0xffff0000, v171
	v_lshlrev_b32_e32 v185, 16, v168
	s_nop 0
	v_cndmask_b32_e64 v239, v182, 0, s[6:7]
	s_waitcnt lgkmcnt(8)
; __device__ __forceinline__ void prep_rwkv_phase(const Params& p, LAS unsigned char* lds, int gw, int ngw, int wave, int lane) {
;     ...
;         f32x4 accD[4], accA[4];
; #pragma unroll
;         for (int i = 0; i < 4; ++i) {
;             accD[i] = (f32x4){0.f, 0.f, 0.f, 0.f}; accA[i] = accD[i];
; #pragma unroll
;             for (int ks = 0; ks < 2; ++ks) {
;                 const bf16x8 wd = *(const LAS bf16x8*)(WD + (i * 16 + fr) * 72 + ks * 32 + fq * 8), ad = *(const LAS bf16x8*)(act + fr * 264 + ks * 32 + fq * 8);
;                 accD[i] = __builtin_amdgcn_mfma_f32_16x16x32_bf16(wd, ad, accD[i], 0, 0, 0);
;                 const bf16x8 wa = *(const LAS bf16x8*)(WA + (i * 16 + fr) * 72 + ks * 32 + fq * 8), aa = *(const LAS bf16x8*)(act + fr * 264 + 64 + ks * 32 + fq * 8);
;                 accA[i] = __builtin_amdgcn_mfma_f32_16x16x32_bf16(wa, aa, accA[i], 0, 0, 0);
;             }
;         }
;         float nk = 0.f, sbr = 0.f, skr = 0.f, sbo = 0.f;
;         u32x4 kcs[2], kps[2];
; #pragma unroll
;         for (int hf = 0; hf < 2; ++hf) {
;             const int o_ = h * 64 + fq * 16 + hf * 8;
;             kcs[hf] = *(const u32x4*)(prow + 512 + o_); kps[hf] = *(const u32x4*)(pprev + 512 + o_); if (first) kps[hf] = (u32x4){0u, 0u, 0u, 0u};
;             const u32x4 kc = kcs[hf], kp = kps[hf];
; #pragma unroll
;             for (int i2 = 0; i2 < 2; ++i2) { const int c = h * 64 + (2 * hf + i2) * 16 + 4 * fq; const f32x4 muk = *(const LAS f32x4*)(PRM + 512 + c), kk4 = *(const LAS f32x4*)(PRM + 2560 + c);
; #pragma unroll
;                 for (int j = 0; j < 4; ++j) { const int e8 = i2 * 4 + j; const unsigned wc_ = kc[e8 >> 1], wp_ = kp[e8 >> 1];
;                     const float kcur = (e8 & 1) ? bfhi(wc_) : bflo(wc_), kprv = (e8 & 1) ? bfhi(wp_) : bflo(wp_); const float kr_ = (kcur + (kprv - kcur) * muk[j]) * kk4[j]; nk += kr_ * kr_; } }
;         }
;         nk += __shfl_xor(nk, 16); nk += __shfl_xor(nk, 32);
;         const float inv = 1.f / fmaxf(sqrtf(nk), 1e-12f);
;         h16* scp = SC + ((size_t)(b * 8 + h) * SEQ + tin) * 384 + fq * 16;
; #pragma unroll
;         for (int hf = 0; hf < 2; ++hf) {
;             h16x8 owr, odec, ok2, ov, okk, ob;
;             const int o_ = h * 64 + fq * 16 + hf * 8;
;             const u32x4 rc = *(const u32x4*)(prow + o_), kc = kcs[hf], vc = *(const u32x4*)(prow + 1024 + o_);
	v_mfma_f32_16x16x32_bf16 v[74:77], v[44:47], v[156:159], v[36:39]
	v_cndmask_b32_e64 v182, v181, 0, s[6:7]
	v_cndmask_b32_e64 v238, v183, 0, s[6:7]
	s_waitcnt lgkmcnt(7)
	v_mfma_f32_16x16x32_bf16 v[44:47], v[54:57], v[28:31], 0
	v_add_u32_e32 v36, 0x13040, v187
	s_waitcnt lgkmcnt(5)
	v_mfma_f32_16x16x32_bf16 v[70:73], v[62:65], v[78:81], 0
	ds_read_b128 v[188:191], v0
	ds_read_b128 v[40:43], v1
	ds_read_b128 v[62:65], v2
	ds_read_b128 v[36:39], v36
	v_add_u32_e32 v1, 0x11080, v187
	v_cndmask_b32_e64 v0, v32, 0, s[6:7]
	v_mfma_f32_16x16x32_bf16 v[54:57], v[58:61], v[82:85], v[44:47]
	v_lshlrev_b32_e32 v184, 16, v0
	v_and_b32_e32 v0, 0xffff0000, v0
	v_cndmask_b32_e64 v2, v34, 0, s[6:7]
	s_waitcnt lgkmcnt(8)
	v_mfma_f32_16x16x32_bf16 v[58:61], v[66:69], v[156:159], v[70:73]
	s_nop 2
	ds_read_b128 v[70:73], v1
	ds_read_b128 v[44:47], v20
	s_nop 1
	s_waitcnt vmcnt(4)
	v_mov_b64_e32 v[66:67], v[240:241]
	v_mov_b64_e32 v[68:69], v[242:243]
	v_and_b32_e32 v1, 0xffff0000, v169
	s_waitcnt lgkmcnt(9)
	v_mfma_f32_16x16x32_bf16 v[20:23], v[160:163], v[28:31], 0
	v_and_b32_e32 v161, 0xffff0000, v168
	v_sub_f32_e32 v0, v0, v161
	s_waitcnt lgkmcnt(1)
	v_fmac_f32_e32 v161, v71, v0
	v_mfma_f32_16x16x32_bf16 v[28:31], v[24:27], v[78:81], 0
	v_lshlrev_b32_e32 v0, 16, v169
	v_cndmask_b32_e64 v160, v177, 0, s[6:7]
	v_cndmask_b32_e64 v71, v178, 0, s[6:7]
	v_mfma_f32_16x16x32_bf16 v[24:27], v[164:167], v[82:85], v[20:23]
	global_load_dwordx4 v[78:81], v[152:153], off offset:1024
	global_load_dwordx4 v[82:85], v[152:153], off
	s_nop 0
	v_and_b32_e32 v21, 0xffff0000, v33
	v_lshlrev_b32_e32 v20, 16, v33
	v_pk_add_f32 v[20:21], v[20:21], v[0:1] neg_lo:[0,1] neg_hi:[0,1]
	v_mfma_f32_16x16x32_bf16 v[28:31], v[172:175], v[156:159], v[28:31]
	v_fma_f32 v162, v72, v20, v0
	v_fma_f32 v163, v73, v21, v1
	v_add_u32_e32 v0, 0x110c0, v187
	v_add_u32_e32 v1, 0x130c0, v187
	ds_read_b128 v[32:35], v0
	ds_read_b128 v[20:23], v1
	s_waitcnt lgkmcnt(2)
	v_pk_mul_f32 v[158:159], v[46:47], v[162:163]
	v_and_b32_e32 v1, 0xffff0000, v170
	v_lshlrev_b32_e32 v0, 16, v170
	v_and_b32_e32 v47, 0xffff0000, v2
	v_lshlrev_b32_e32 v46, 16, v2
	v_pk_add_f32 v[46:47], v[46:47], v[0:1] neg_lo:[0,1] neg_hi:[0,1]
	v_lshlrev_b32_e32 v172, 16, v171
	s_waitcnt lgkmcnt(1)
	v_pk_fma_f32 v[164:165], v[32:33], v[46:47], v[0:1]
	v_lshlrev_b32_e32 v0, 16, v48
	v_sub_f32_e32 v0, v0, v172
	v_add_u32_e32 v32, 0x12000, v187
	v_mul_f32_e32 v150, v34, v0
	v_and_b32_e32 v0, 0xffff0000, v48
	ds_read_b128 v[46:49], v32
	v_add_u32_e32 v34, 0x12800, v187
	v_cndmask_b32_e64 v173, v176, 0, s[6:7]
	ds_read_b128 v[174:177], v34
	v_add_u32_e32 v32, 0x10800, v187
	s_waitcnt lgkmcnt(1)
	v_add_f32_e32 v34, v90, v46
	v_mul_f32_e32 v34, 0xbfb8aa3b, v34
	v_exp_f32_e32 v34, v34
	v_add_u32_e32 v33, 0x11800, v187
	ds_read_b128 v[192:195], v32
	ds_read_b128 v[196:199], v33
	s_waitcnt lgkmcnt(2)
	v_add_f32_e32 v72, v86, v174
	v_add_f32_e32 v33, 1.0, v34
	v_rcp_f32_e32 v46, v33
	v_mul_f32_e32 v72, 0xbfb8aa3b, v72
	v_add_f32_e32 v47, v91, v47
	v_exp_f32_e32 v72, v72
	v_mul_f32_e32 v47, 0xbfb8aa3b, v47
	v_exp_f32_e32 v47, v47
	v_mul_f32_e32 v46, 0xbf1b4598, v46
	v_mul_f32_e32 v46, 0x3fb8aa3b, v46
	v_cndmask_b32_e64 v73, v180, 0, s[6:7]
	v_exp_f32_e32 v180, v46
	v_add_f32_e32 v46, 1.0, v72
	v_rcp_f32_e32 v170, v46
	v_add_f32_e32 v46, 1.0, v47
	v_rcp_f32_e32 v46, v46
	v_add_f32_e32 v47, v87, v175
	v_mul_f32_e32 v47, 0xbfb8aa3b, v47
	v_exp_f32_e32 v47, v47
	v_mul_f32_e32 v46, 0xbf1b4598, v46
	v_mul_f32_e32 v46, 0x3fb8aa3b, v46
	v_exp_f32_e32 v181, v46
	v_add_f32_e32 v46, 1.0, v47
	v_rcp_f32_e32 v171, v46
	v_lshlrev_b32_e32 v72, 16, v73
	v_and_b32_e32 v73, 0xffff0000, v73
	v_sub_f32_e32 v0, v0, v132
	v_add_u32_e32 v32, 0x13800, v187
	v_add_u32_e32 v33, 0x14000, v187
	v_pk_mul_f32 v[156:157], v[20:21], v[164:165]
	v_mul_f32_e32 v20, v35, v0
	ds_read_b128 v[200:203], v32
	ds_read_b128 v[32:35], v33
	v_lshlrev_b32_e32 v90, 16, v228
	v_and_b32_e32 v91, 0xffff0000, v228
	v_cndmask_b32_e64 v21, v179, 0, s[6:7]
	v_lshlrev_b32_e32 v174, 16, v173
	v_and_b32_e32 v175, 0xffff0000, v173
	v_and_b32_e32 v1, 64, v227
	v_xor_b32_e32 v0, 16, v227
	v_add_u32_e32 v1, 64, v1
	v_cmp_lt_i32_e32 vcc, v0, v1
	v_pk_mul_f32 v[166:167], v[158:159], v[158:159]
	v_mov_b32_e32 v173, v133
	v_cndmask_b32_e32 v0, v227, v0, vcc
	v_lshlrev_b32_e32 v145, 2, v0
	v_xor_b32_e32 v0, 32, v227
	v_cmp_lt_i32_e32 vcc, v0, v1
	s_waitcnt vmcnt(0)
	v_lshlrev_b32_e32 v46, 16, v82
	v_and_b32_e32 v47, 0xffff0000, v82
	v_pk_add_f32 v[72:73], v[72:73], v[46:47] neg_lo:[0,1] neg_hi:[0,1]
	v_cndmask_b32_e32 v0, v227, v0, vcc
	s_waitcnt lgkmcnt(3)
	v_pk_fma_f32 v[86:87], v[192:193], v[72:73], v[46:47]
	v_lshlrev_b32_e32 v2, 2, v0
	v_pk_mul_f32 v[46:47], v[86:87], v[180:181]
	v_lshl_add_u64 v[0:1], s[92:93], 0, v[140:141]
	v_cvt_pk_f16_f32 v72, v46, v47
	v_lshlrev_b32_e32 v46, 16, v78
	v_and_b32_e32 v47, 0xffff0000, v78
	v_pk_add_f32 v[90:91], v[90:91], v[46:47] neg_lo:[0,1] neg_hi:[0,1]
	v_pk_mul_f32 v[168:169], v[156:157], v[156:157]
	v_pk_fma_f32 v[178:179], v[188:189], v[90:91], v[46:47]
	v_pk_add_f32 v[46:47], v[170:171], -1.0 op_sel_hi:[1,0]
	s_waitcnt lgkmcnt(1)
; #define LAS __attribute__((address_space(3)))
; __device__ __forceinline__ float fast_sigmoid(float x) { return __builtin_amdgcn_rcpf(1.f + __expf(-x)); }
; __device__ __forceinline__ void prep_rwkv_phase(const Params& p, LAS unsigned char* lds, int gw, int ngw, int wave, int lane) {
;     ...
;         for (int hf = 0; hf < 2; ++hf) {
;             h16x8 owr, odec, ok2, ov, okk, ob;
;             const int o_ = h * 64 + fq * 16 + hf * 8;
;             const u32x4 rc = *(const u32x4*)(prow + o_), kc = kcs[hf], vc = *(const u32x4*)(prow + 1024 + o_);
;             u32x4 rp = *(const u32x4*)(pprev + o_), vp = *(const u32x4*)(pprev + 1024 + o_); const u32x4 kp = kps[hf];
;             if (first) { rp = (u32x4){0u, 0u, 0u, 0u}; vp = rp; }
; #pragma unroll
;             for (int i2 = 0; i2 < 2; ++i2) {
;                 const int i = 2 * hf + i2, c = h * 64 + i * 16 + 4 * fq;
;                 const f32x4 mur = *(const LAS f32x4*)(PRM + c), muk = *(const LAS f32x4*)(PRM + 512 + c), muv = *(const LAS f32x4*)(PRM + 1024 + c);
;                 const f32x4 w04 = *(const LAS f32x4*)(PRM + 1536 + c), a04 = *(const LAS f32x4*)(PRM + 2048 + c), kk4 = *(const LAS f32x4*)(PRM + 2560 + c), ka4 = *(const LAS f32x4*)(PRM + 3072 + c), rk4 = *(const LAS f32x4*)(PRM + 3584 + c);
; #pragma unroll
;                 for (int j = 0; j < 4; ++j) {
;                     const int e8 = i2 * 4 + j, e = hf * 8 + e8; const unsigned wsel = (e8 >> 1); const bool hiw = e8 & 1;
;     ...
;                     const float rcur = PREP_GET(rc), rprv = PREP_GET(rp), kcur = PREP_GET(kc), kprv = PREP_GET(kp), vcur = PREP_GET(vc), vprv = PREP_GET(vp);
;     ...
;                     const float r = rcur + (rprv - rcur) * mur[j], k = kcur + (kprv - kcur) * muk[j], v = vcur + (vprv - vcur) * muv[j];
;                     const float dec = __expf(-0.60653066f * fast_sigmoid(w04[j] + accD[i][j]));
;                     const float a = fast_sigmoid(a04[j] + accA[i][j]);
;                     const float kraw = k * kk4[j], k2 = k * (1.f + (a - 1.f) * ka4[j]);
;                     const float kkn = kraw * inv, bn = kkn * a; sbr += bn * r; skr += k2 * r; sbo += r * k2 * rk4[j];
;                     okk[e8] = (h16)kkn; ob[e8] = (h16)bn;
;                     owr[e8] = (h16)(dec * r); odec[e8] = (h16)dec; ok2[e8] = (h16)k2; ov[e8] = (h16)v;
;                 }
;             }
	v_pk_fma_f32 v[46:47], v[200:201], v[46:47], 1.0 op_sel_hi:[1,1,0]
	s_nop 0
	v_pk_mul_f32 v[90:91], v[178:179], v[46:47]
	v_add_f32_e32 v47, v92, v48
	v_mul_f32_e32 v47, 0xbfb8aa3b, v47
	v_exp_f32_e32 v48, v47
	v_lshlrev_b32_e32 v46, 16, v66
	v_and_b32_e32 v47, 0xffff0000, v66
	v_pk_add_f32 v[174:175], v[174:175], v[46:47] neg_lo:[0,1] neg_hi:[0,1]
	v_add_f32_e32 v48, 1.0, v48
	v_rcp_f32_e32 v48, v48
	v_pk_fma_f32 v[46:47], v[196:197], v[174:175], v[46:47]
	v_lshlrev_b32_e32 v174, 16, v80
	v_cvt_pk_f16_f32 v66, v46, v47
	v_add_f32_e32 v47, v88, v176
	v_mul_f32_e32 v46, 0xbf1b4598, v48
	v_mul_f32_e32 v47, 0xbfb8aa3b, v47
	v_add_f32_e32 v48, v93, v49
	v_exp_f32_e32 v47, v47
	v_mul_f32_e32 v48, 0xbfb8aa3b, v48
	v_exp_f32_e32 v48, v48
	v_mul_f32_e32 v46, 0x3fb8aa3b, v46
	v_exp_f32_e32 v236, v46
	v_add_f32_e32 v46, 1.0, v47
	v_rcp_f32_e32 v176, v46
	v_add_f32_e32 v46, 1.0, v48
	v_rcp_f32_e32 v46, v46
	v_add_f32_e32 v47, v89, v177
	v_mul_f32_e32 v47, 0xbfb8aa3b, v47
	v_exp_f32_e32 v47, v47
	v_mul_f32_e32 v46, 0xbf1b4598, v46
	v_mul_f32_e32 v46, 0x3fb8aa3b, v46
	v_exp_f32_e32 v237, v46
	v_add_f32_e32 v46, 1.0, v47
	v_rcp_f32_e32 v177, v46
	v_lshlrev_b32_e32 v46, 16, v83
	v_and_b32_e32 v47, 0xffff0000, v83
	v_lshlrev_b32_e32 v48, 16, v182
	v_and_b32_e32 v49, 0xffff0000, v182
	v_pk_add_f32 v[48:49], v[48:49], v[46:47] neg_lo:[0,1] neg_hi:[0,1]
	v_and_b32_e32 v175, 0xffff0000, v80
	v_pk_fma_f32 v[82:83], v[194:195], v[48:49], v[46:47]
	v_lshlrev_b32_e32 v48, 16, v186
	v_pk_mul_f32 v[46:47], v[82:83], v[236:237]
	v_and_b32_e32 v49, 0xffff0000, v186
	v_cvt_pk_f16_f32 v73, v46, v47
	v_lshlrev_b32_e32 v46, 16, v79
	v_and_b32_e32 v47, 0xffff0000, v79
	v_pk_add_f32 v[48:49], v[48:49], v[46:47] neg_lo:[0,1] neg_hi:[0,1]
	v_lshlrev_b32_e32 v92, 16, v239
	v_pk_fma_f32 v[188:189], v[190:191], v[48:49], v[46:47]
	v_pk_add_f32 v[46:47], v[176:177], -1.0 op_sel_hi:[1,0]
	v_lshlrev_b32_e32 v48, 16, v160
	v_pk_fma_f32 v[46:47], v[202:203], v[46:47], 1.0 op_sel_hi:[1,1,0]
	v_and_b32_e32 v49, 0xffff0000, v160
	v_pk_mul_f32 v[88:89], v[188:189], v[46:47]
	v_lshlrev_b32_e32 v46, 16, v67
	v_and_b32_e32 v47, 0xffff0000, v67
	v_pk_add_f32 v[48:49], v[48:49], v[46:47] neg_lo:[0,1] neg_hi:[0,1]
	v_and_b32_e32 v93, 0xffff0000, v239
	v_pk_fma_f32 v[46:47], v[198:199], v[48:49], v[46:47]
	v_add_u32_e32 v48, 0x12840, v187
	v_cvt_pk_f16_f32 v67, v46, v47
	v_add_u32_e32 v46, 0x12040, v187
	ds_read_b128 v[190:193], v46
	ds_read_b128 v[194:197], v48
	v_add_u32_e32 v46, 0x10840, v187
	v_add_u32_e32 v47, 0x11840, v187
	ds_read_b128 v[198:201], v46
	ds_read_b128 v[228:231], v47
	s_waitcnt lgkmcnt(3)
	v_add_f32_e32 v48, v50, v190
	s_waitcnt lgkmcnt(2)
	v_add_f32_e32 v74, v74, v194
	v_mul_f32_e32 v74, 0xbfb8aa3b, v74
	v_exp_f32_e32 v74, v74
	v_mul_f32_e32 v48, 0xbfb8aa3b, v48
	v_exp_f32_e32 v48, v48
	v_add_u32_e32 v46, 0x13840, v187
	v_add_f32_e32 v74, 1.0, v74
	v_rcp_f32_e32 v182, v74
	v_add_f32_e32 v74, v75, v195
	v_mul_f32_e32 v74, 0xbfb8aa3b, v74
	v_exp_f32_e32 v74, v74
	v_add_f32_e32 v47, 1.0, v48
	v_rcp_f32_e32 v50, v47
	v_add_u32_e32 v47, 0x14040, v187
	v_add_f32_e32 v74, 1.0, v74
	v_rcp_f32_e32 v183, v74
	ds_read_b128 v[232:235], v46
	ds_read_b128 v[46:49], v47
	v_add_f32_e32 v51, v51, v191
	v_lshlrev_b32_e32 v190, 16, v151
	v_and_b32_e32 v191, 0xffff0000, v151
	v_pk_add_f32 v[190:191], v[190:191], v[174:175] neg_lo:[0,1] neg_hi:[0,1]
	v_add_f32_e32 v52, v52, v192
	v_pk_fma_f32 v[202:203], v[62:63], v[190:191], v[174:175]
	v_pk_add_f32 v[62:63], v[182:183], -1.0 op_sel_hi:[1,0]
	v_lshlrev_b32_e32 v190, 16, v71
	s_waitcnt lgkmcnt(1)
	v_pk_fma_f32 v[62:63], v[232:233], v[62:63], 1.0 op_sel_hi:[1,1,0]
	v_and_b32_e32 v191, 0xffff0000, v71
	v_pk_mul_f32 v[174:175], v[202:203], v[62:63]
	v_lshlrev_b32_e32 v62, 16, v68
	v_and_b32_e32 v63, 0xffff0000, v68
	v_pk_add_f32 v[190:191], v[190:191], v[62:63] neg_lo:[0,1] neg_hi:[0,1]
	v_add_f32_e32 v53, v53, v193
	v_pk_fma_f32 v[62:63], v[190:191], v[228:229], v[62:63]
	v_mul_f32_e32 v51, 0xbfb8aa3b, v51
	v_cvt_pk_f16_f32 v68, v62, v63
	v_add_f32_e32 v62, v76, v196
	v_mul_f32_e32 v52, 0xbfb8aa3b, v52
	v_mul_f32_e32 v62, 0xbfb8aa3b, v62
	v_mul_f32_e32 v53, 0xbfb8aa3b, v53
	v_exp_f32_e32 v51, v51
	v_exp_f32_e32 v52, v52
	v_exp_f32_e32 v62, v62
	v_exp_f32_e32 v53, v53
	v_add_f32_e32 v51, 1.0, v51
	v_add_f32_e32 v52, 1.0, v52
	v_add_f32_e32 v62, 1.0, v62
	v_add_f32_e32 v53, 1.0, v53
	v_rcp_f32_e32 v51, v51
	v_rcp_f32_e32 v52, v52
	v_rcp_f32_e32 v196, v62
	v_rcp_f32_e32 v53, v53
	v_add_f32_e32 v62, v77, v197
	v_mul_f32_e32 v62, 0xbfb8aa3b, v62
	v_exp_f32_e32 v62, v62
	v_mul_f32_e32 v50, 0xbf1b4598, v50
	v_mul_f32_e32 v51, 0xbf1b4598, v51
	v_mul_f32_e32 v52, 0xbf1b4598, v52
	v_mul_f32_e32 v53, 0xbf1b4598, v53
	v_mul_f32_e32 v50, 0x3fb8aa3b, v50
	v_mul_f32_e32 v51, 0x3fb8aa3b, v51
	v_mul_f32_e32 v52, 0x3fb8aa3b, v52
	v_mul_f32_e32 v53, 0x3fb8aa3b, v53
	v_exp_f32_e32 v50, v50
	v_exp_f32_e32 v51, v51
	v_exp_f32_e32 v52, v52
	v_exp_f32_e32 v53, v53
	v_add_f32_e32 v62, 1.0, v62
	v_lshlrev_b32_e32 v74, 16, v84
	v_and_b32_e32 v75, 0xffff0000, v84
	v_rcp_f32_e32 v197, v62
	v_lshlrev_b32_e32 v62, 16, v85
	v_and_b32_e32 v63, 0xffff0000, v85
	v_lshlrev_b32_e32 v76, 16, v238
	v_and_b32_e32 v77, 0xffff0000, v238
	v_pk_add_f32 v[92:93], v[92:93], v[74:75] neg_lo:[0,1] neg_hi:[0,1]
	v_pk_add_f32 v[76:77], v[76:77], v[62:63] neg_lo:[0,1] neg_hi:[0,1]
	v_pk_fma_f32 v[92:93], v[92:93], v[198:199], v[74:75]
	v_pk_fma_f32 v[84:85], v[76:77], v[200:201], v[62:63]
	v_pk_mul_f32 v[74:75], v[92:93], v[50:51]
	v_pk_mul_f32 v[62:63], v[84:85], v[52:53]
	v_cvt_pk_f16_f32 v74, v74, v75
	v_cvt_pk_f16_f32 v75, v62, v63
	v_lshlrev_b32_e32 v62, 16, v81
	v_and_b32_e32 v63, 0xffff0000, v81
	v_lshlrev_b32_e32 v76, 16, v130
	v_and_b32_e32 v77, 0xffff0000, v130
	v_pk_add_f32 v[76:77], v[76:77], v[62:63] neg_lo:[0,1] neg_hi:[0,1]
	v_cvt_pk_f16_f32 v53, v52, v53
	v_pk_fma_f32 v[232:233], v[64:65], v[76:77], v[62:63]
	v_pk_add_f32 v[62:63], v[196:197], -1.0 op_sel_hi:[1,0]
	v_cvt_pk_f16_f32 v52, v50, v51
	v_pk_fma_f32 v[62:63], v[234:235], v[62:63], 1.0 op_sel_hi:[1,1,0]
	v_cvt_pk_f16_f32 v50, v180, v181
	v_pk_mul_f32 v[180:181], v[232:233], v[62:63]
	v_lshlrev_b32_e32 v62, 16, v69
	v_and_b32_e32 v63, 0xffff0000, v69
	v_lshlrev_b32_e32 v64, 16, v21
	v_and_b32_e32 v65, 0xffff0000, v21
	v_pk_add_f32 v[64:65], v[64:65], v[62:63] neg_lo:[0,1] neg_hi:[0,1]
	v_cvt_pk_f16_f32 v78, v90, v91
	v_pk_fma_f32 v[62:63], v[64:65], v[230:231], v[62:63]
	v_cvt_pk_f16_f32 v79, v88, v89
	v_cvt_pk_f16_f32 v80, v174, v175
	v_cvt_pk_f16_f32 v51, v236, v237
	v_cvt_pk_f16_f32 v81, v180, v181
	v_cvt_pk_f16_f32 v69, v62, v63
	global_store_dwordx4 v[0:1], v[72:75], off offset:-256
	global_store_dwordx4 v[0:1], v[50:53], off offset:-128
	global_store_dwordx4 v[0:1], v[78:81], off offset:128
	global_store_dwordx4 v[0:1], v[66:69], off offset:256
	v_add_u32_e32 v21, 0x12080, v187
	ds_read_b128 v[72:75], v21
	v_add_u32_e32 v51, 0x12880, v187
	ds_read_b128 v[78:81], v51
	v_add_u32_e32 v21, 0x10880, v187
	v_add_u32_e32 v50, 0x11880, v187
	s_waitcnt lgkmcnt(1)
; __device__ __forceinline__ void prep_rwkv_phase(const Params& p, LAS unsigned char* lds, int gw, int ngw, int wave, int lane) {
;     ...
;         nk += __shfl_xor(nk, 16); nk += __shfl_xor(nk, 32);
;         const float inv = 1.f / fmaxf(sqrtf(nk), 1e-12f);
;         h16* scp = SC + ((size_t)(b * 8 + h) * SEQ + tin) * 384 + fq * 16;
; #pragma unroll
;         for (int hf = 0; hf < 2; ++hf) {
;             h16x8 owr, odec, ok2, ov, okk, ob;
;             const int o_ = h * 64 + fq * 16 + hf * 8;
;             const u32x4 rc = *(const u32x4*)(prow + o_), kc = kcs[hf], vc = *(const u32x4*)(prow + 1024 + o_);
;             u32x4 rp = *(const u32x4*)(pprev + o_), vp = *(const u32x4*)(pprev + 1024 + o_); const u32x4 kp = kps[hf];
;             if (first) { rp = (u32x4){0u, 0u, 0u, 0u}; vp = rp; }
; #pragma unroll
;             for (int i2 = 0; i2 < 2; ++i2) {
;                 const int i = 2 * hf + i2, c = h * 64 + i * 16 + 4 * fq;
;                 const f32x4 mur = *(const LAS f32x4*)(PRM + c), muk = *(const LAS f32x4*)(PRM + 512 + c), muv = *(const LAS f32x4*)(PRM + 1024 + c);
;                 const f32x4 w04 = *(const LAS f32x4*)(PRM + 1536 + c), a04 = *(const LAS f32x4*)(PRM + 2048 + c), kk4 = *(const LAS f32x4*)(PRM + 2560 + c), ka4 = *(const LAS f32x4*)(PRM + 3072 + c), rk4 = *(const LAS f32x4*)(PRM + 3584 + c);
; #pragma unroll
;                 for (int j = 0; j < 4; ++j) {
;                     const int e8 = i2 * 4 + j, e = hf * 8 + e8; const unsigned wsel = (e8 >> 1); const bool hiw = e8 & 1;
;     ...
;                     const float rcur = PREP_GET(rc), rprv = PREP_GET(rp), kcur = PREP_GET(kc), kprv = PREP_GET(kp), vcur = PREP_GET(vc), vprv = PREP_GET(vp);
;     ...
;                     const float r = rcur + (rprv - rcur) * mur[j], k = kcur + (kprv - kcur) * muk[j], v = vcur + (vprv - vcur) * muv[j];
;                     const float dec = __expf(-0.60653066f * fast_sigmoid(w04[j] + accD[i][j]));
;                     const float a = fast_sigmoid(a04[j] + accA[i][j]);
;                     const float kraw = k * kk4[j], k2 = k * (1.f + (a - 1.f) * ka4[j]);
;                     const float kkn = kraw * inv, bn = kkn * a; sbr += bn * r; skr += k2 * r; sbo += r * k2 * rk4[j];
;                     okk[e8] = (h16)kkn; ob[e8] = (h16)bn;
;                     owr[e8] = (h16)(dec * r); odec[e8] = (h16)dec; ok2[e8] = (h16)k2; ov[e8] = (h16)v;
;                 }
	v_add_f32_e32 v51, v54, v72
	v_mul_f32_e32 v51, 0xbfb8aa3b, v51
	v_exp_f32_e32 v54, v51
	s_waitcnt lgkmcnt(0)
	v_add_f32_e32 v58, v58, v78
	v_mul_f32_e32 v58, 0xbfb8aa3b, v58
	v_exp_f32_e32 v58, v58
	v_add_f32_e32 v54, 1.0, v54
	v_rcp_f32_e32 v54, v54
	ds_read_b128 v[62:65], v21
	ds_read_b128 v[50:53], v50
	v_add_u32_e32 v21, 0x13880, v187
	v_add_u32_e32 v66, 0x14080, v187
	ds_read_b128 v[228:231], v21
	ds_read_b128 v[66:69], v66
	v_add_f32_e32 v21, 1.0, v58
	v_rcp_f32_e32 v186, v21
	v_mul_f32_e32 v21, 0xbf1b4598, v54
	v_mov_b32_e32 v54, v185
	v_pk_add_f32 v[76:77], v[184:185], v[54:55] neg_lo:[0,1] neg_hi:[0,1]
	v_add_f32_e32 v54, v59, v79
	v_mul_f32_e32 v21, 0x3fb8aa3b, v21
	v_mul_f32_e32 v54, 0xbfb8aa3b, v54
	v_exp_f32_e32 v78, v21
	v_add_f32_e32 v21, -1.0, v186
	v_exp_f32_e32 v54, v54
	v_mov_b32_e32 v77, v21
	v_add_f32_e32 v21, v55, v73
	v_mul_f32_e32 v21, 0xbfb8aa3b, v21
	v_exp_f32_e32 v21, v21
	v_add_f32_e32 v54, 1.0, v54
	v_rcp_f32_e32 v160, v54
	v_add_f32_e32 v54, v56, v74
	v_mul_f32_e32 v54, 0xbfb8aa3b, v54
	v_add_f32_e32 v21, 1.0, v21
	v_exp_f32_e32 v54, v54
	v_rcp_f32_e32 v21, v21
	v_add_f32_e32 v55, v60, v80
	v_mul_f32_e32 v55, 0xbfb8aa3b, v55
	v_exp_f32_e32 v55, v55
	v_add_f32_e32 v54, 1.0, v54
	v_mul_f32_e32 v21, 0xbf1b4598, v21
	v_rcp_f32_e32 v54, v54
	v_mul_f32_e32 v21, 0x3fb8aa3b, v21
	v_exp_f32_e32 v79, v21
	v_add_f32_e32 v21, -1.0, v160
	s_waitcnt lgkmcnt(1)
	v_fma_f32 v201, v229, v21, 1.0
	v_add_f32_e32 v21, 1.0, v55
	v_rcp_f32_e32 v184, v21
	v_mul_f32_e32 v21, 0xbf1b4598, v54
	v_add_f32_e32 v54, v57, v75
	v_mul_f32_e32 v54, 0xbfb8aa3b, v54
	v_exp_f32_e32 v54, v54
	v_add_f32_e32 v55, v61, v81
	v_mul_f32_e32 v55, 0xbfb8aa3b, v55
	v_exp_f32_e32 v55, v55
	v_add_f32_e32 v54, 1.0, v54
	v_rcp_f32_e32 v54, v54
	v_mul_f32_e32 v21, 0x3fb8aa3b, v21
	v_exp_f32_e32 v80, v21
	v_add_f32_e32 v21, -1.0, v184
	v_fma_f32 v195, v230, v21, 1.0
	v_add_f32_e32 v21, 1.0, v55
	v_rcp_f32_e32 v190, v21
	v_mul_f32_e32 v21, 0xbf1b4598, v54
	v_mul_f32_e32 v21, 0x3fb8aa3b, v21
	v_mov_b32_e32 v71, v228
	v_mov_b32_e32 v130, v185
	v_exp_f32_e32 v81, v21
	v_add_u32_e32 v21, 0x120c0, v187
	v_pk_fma_f32 v[192:193], v[70:71], v[76:77], v[130:131]
	v_add_u32_e32 v54, 0x128c0, v187
	ds_read_b128 v[70:73], v21
	ds_read_b128 v[74:77], v54
	v_add_u32_e32 v21, 0x138c0, v187
	v_add_u32_e32 v54, 0x140c0, v187
	ds_read_b128 v[58:61], v21
	ds_read_b128 v[54:57], v54
	s_waitcnt lgkmcnt(3)
	v_add_f32_e32 v21, v24, v70
	v_mul_f32_e32 v24, 0xbfb8aa3b, v21
	s_waitcnt lgkmcnt(2)
	v_add_f32_e32 v21, v31, v77
	v_add_f32_e32 v30, v30, v76
	v_pk_mul_f32 v[228:229], v[40:41], v[178:179]
	v_mul_f32_e32 v21, 0xbfb8aa3b, v21
	v_mul_f32_e32 v30, 0xbfb8aa3b, v30
	v_pk_mul_f32 v[40:41], v[228:229], v[228:229]
	v_pk_mul_f32 v[188:189], v[42:43], v[188:189]
	v_exp_f32_e32 v21, v21
	v_exp_f32_e32 v30, v30
	v_pk_mul_f32 v[42:43], v[188:189], v[188:189]
	v_add_f32_e32 v40, v40, v41
	v_pk_mul_f32 v[202:203], v[36:37], v[202:203]
	v_add_f32_e32 v40, v42, v40
	v_pk_mul_f32 v[36:37], v[202:203], v[202:203]
	v_add_f32_e32 v40, v43, v40
	v_pk_mul_f32 v[232:233], v[38:39], v[232:233]
	v_add_f32_e32 v36, v36, v40
	v_add_f32_e32 v21, 1.0, v21
	v_add_f32_e32 v30, 1.0, v30
	v_pk_mul_f32 v[38:39], v[232:233], v[232:233]
	v_mov_b32_e32 v178, v192
	v_mov_b32_e32 v179, v161
	v_add_f32_e32 v36, v37, v36
	v_rcp_f32_e32 v21, v21
	v_rcp_f32_e32 v151, v30
	v_pk_mul_f32 v[178:179], v[44:45], v[178:179]
	v_add_f32_e32 v36, v38, v36
	v_pk_mul_f32 v[234:235], v[178:179], v[178:179]
	v_add_f32_e32 v36, v39, v36
	v_add_f32_e32 v36, v234, v36
	v_add_f32_e32 v36, v235, v36
	v_pk_add_f32 v[30:31], v[20:21], v[132:133]
	v_mov_b32_e32 v76, v23
	s_waitcnt lgkmcnt(1)
	v_mov_b32_e32 v77, v61
	v_pk_add_f32 v[44:45], v[150:151], v[172:173]
	v_mov_b32_e32 v23, v60
	v_add_f32_e32 v36, v166, v36
	v_pk_mul_f32 v[198:199], v[76:77], v[30:31]
	v_pk_mul_f32 v[60:61], v[22:23], v[44:45]
	v_add_f32_e32 v36, v167, v36
	v_mov_b32_e32 v172, v198
	v_mov_b32_e32 v173, v60
	v_add_f32_e32 v36, v168, v36
	v_pk_mul_f32 v[172:173], v[172:173], v[172:173]
	v_add_f32_e32 v36, v169, v36
	v_add_f32_e32 v36, v173, v36
	v_add_f32_e32 v36, v172, v36
	ds_bpermute_b32 v37, v145, v36
	v_exp_f32_e32 v24, v24
	v_add_f32_e32 v28, v28, v74
	v_mul_f32_e32 v28, 0xbfb8aa3b, v28
	v_exp_f32_e32 v28, v28
	s_waitcnt lgkmcnt(0)
	v_add_f32_e32 v36, v36, v37
	ds_bpermute_b32 v37, v2, v36
	v_add_f32_e32 v24, 1.0, v24
	v_rcp_f32_e32 v24, v24
	v_add_f32_e32 v130, -1.0, v190
	v_fma_f32 v167, v231, v130, 1.0
	s_waitcnt lgkmcnt(0)
	v_add_f32_e32 v36, v36, v37
	v_mul_f32_e32 v37, 0x4f800000, v36
	v_cmp_gt_f32_e32 vcc, s29, v36
	v_mul_f32_e32 v132, 0xbf1b4598, v24
	v_add_f32_e32 v24, 1.0, v28
	v_cndmask_b32_e32 v70, v36, v37, vcc
	v_sqrt_f32_e32 v74, v70
	v_add_u32_e32 v38, 0x108c0, v187
	v_add_u32_e32 v39, 0x118c0, v187
	ds_read_b128 v[40:43], v38
	ds_read_b128 v[36:39], v39
	v_add_u32_e32 v28, -1, v74
	v_fma_f32 v130, -v28, v74, v70
	v_cmp_ge_f32_e64 s[8:9], 0, v130
	v_add_u32_e32 v130, 1, v74
	v_add_f32_e32 v26, v26, v72
	v_cndmask_b32_e64 v28, v74, v28, s[8:9]
	v_fma_f32 v74, -v130, v74, v70
	v_cmp_lt_f32_e64 s[8:9], 0, v74
	v_add_f32_e32 v27, v27, v73
	v_mov_b32_e32 v185, v162
	v_cndmask_b32_e64 v28, v28, v130, s[8:9]
	v_mul_f32_e32 v74, 0x37800000, v28
	v_cndmask_b32_e32 v28, v28, v74, vcc
	v_cmp_class_f32_e32 vcc, v70, v223
	v_mov_b32_e32 v191, v163
	v_mov_b32_e32 v163, v90
	v_cndmask_b32_e32 v28, v28, v70, vcc
	v_max_f32_e32 v70, 0x2b8cbccc, v28
	v_div_scale_f32 v74, s[8:9], v70, v70, 1.0
	v_rcp_f32_e32 v130, v74
	v_rcp_f32_e32 v28, v24
	v_add_f32_e32 v24, v25, v71
	v_mul_f32_e32 v150, 0xbfb8aa3b, v24
	v_fma_f32 v24, -v74, v130, 1.0
	v_fmac_f32_e32 v130, v24, v130
	v_div_scale_f32 v24, vcc, 1.0, v70, 1.0
	v_mul_f32_e32 v25, v24, v130
	v_fma_f32 v71, -v74, v25, v24
	v_fmac_f32_e32 v25, v71, v130
	v_fma_f32 v24, -v74, v25, v24
	v_div_fmas_f32 v24, v24, v130, v25
	v_div_fixup_f32 v130, v24, v70, 1.0
	v_pk_mul_f32 v[24:25], v[228:229], v[130:131] op_sel_hi:[1,0]
	v_pk_mul_f32 v[70:71], v[188:189], v[130:131] op_sel_hi:[1,0]
	v_pk_mul_f32 v[188:189], v[202:203], v[130:131] op_sel_hi:[1,0]
	v_pk_mul_f32 v[202:203], v[232:233], v[130:131] op_sel_hi:[1,0]
	v_pk_mul_f32 v[172:173], v[170:171], v[24:25]
	v_pk_mul_f32 v[176:177], v[176:177], v[70:71]
	v_pk_mul_f32 v[182:183], v[188:189], v[182:183]
	v_pk_mul_f32 v[196:197], v[202:203], v[196:197]
	v_cvt_pk_f16_f32 v231, v202, v203
	v_cvt_pk_f16_f32 v230, v188, v189
	v_cvt_pk_f16_f32 v229, v70, v71
	v_cvt_pk_f16_f32 v228, v24, v25
	v_cvt_pk_f16_f32 v168, v172, v173
	v_cvt_pk_f16_f32 v169, v176, v177
	v_cvt_pk_f16_f32 v170, v182, v183
	v_cvt_pk_f16_f32 v171, v196, v197
	global_store_dwordx4 v[0:1], v[228:231], off offset:-384
	global_store_dwordx4 v[0:1], v[168:171], off
	s_nop 1
	s_waitcnt vmcnt(9)
; #define LAS __attribute__((address_space(3)))
; __device__ __forceinline__ float fast_sigmoid(float x) { return __builtin_amdgcn_rcpf(1.f + __expf(-x)); }
; #define PREP_GET(arr) ({ const unsigned w_ = arr[wsel]; hiw ? bfhi(w_) : bflo(w_); })
; __device__ __forceinline__ void prep_rwkv_phase(const Params& p, LAS unsigned char* lds, int gw, int ngw, int wave, int lane) {
;     ...
;         for (int hf = 0; hf < 2; ++hf) {
;             h16x8 owr, odec, ok2, ov, okk, ob;
;             const int o_ = h * 64 + fq * 16 + hf * 8;
;             const u32x4 rc = *(const u32x4*)(prow + o_), kc = kcs[hf], vc = *(const u32x4*)(prow + 1024 + o_);
;             u32x4 rp = *(const u32x4*)(pprev + o_), vp = *(const u32x4*)(pprev + 1024 + o_); const u32x4 kp = kps[hf];
;             if (first) { rp = (u32x4){0u, 0u, 0u, 0u}; vp = rp; }
; #pragma unroll
;             for (int i2 = 0; i2 < 2; ++i2) {
;                 const int i = 2 * hf + i2, c = h * 64 + i * 16 + 4 * fq;
;                 const f32x4 mur = *(const LAS f32x4*)(PRM + c), muk = *(const LAS f32x4*)(PRM + 512 + c), muv = *(const LAS f32x4*)(PRM + 1024 + c);
;                 const f32x4 w04 = *(const LAS f32x4*)(PRM + 1536 + c), a04 = *(const LAS f32x4*)(PRM + 2048 + c), kk4 = *(const LAS f32x4*)(PRM + 2560 + c), ka4 = *(const LAS f32x4*)(PRM + 3072 + c), rk4 = *(const LAS f32x4*)(PRM + 3584 + c);
; #pragma unroll
;                 for (int j = 0; j < 4; ++j) {
;                     const int e8 = i2 * 4 + j, e = hf * 8 + e8; const unsigned wsel = (e8 >> 1); const bool hiw = e8 & 1;
;     ...
;                     const float rcur = PREP_GET(rc), rprv = PREP_GET(rp), kcur = PREP_GET(kc), kprv = PREP_GET(kp), vcur = PREP_GET(vc), vprv = PREP_GET(vp);
;     ...
;                     const float r = rcur + (rprv - rcur) * mur[j], k = kcur + (kprv - kcur) * muk[j], v = vcur + (vprv - vcur) * muv[j];
;                     const float dec = __expf(-0.60653066f * fast_sigmoid(w04[j] + accD[i][j]));
;                     const float a = fast_sigmoid(a04[j] + accA[i][j]);
;                     const float kraw = k * kk4[j], k2 = k * (1.f + (a - 1.f) * ka4[j]);
;                     const float kkn = kraw * inv, bn = kkn * a; sbr += bn * r; skr += k2 * r; sbo += r * k2 * rk4[j];
;                     okk[e8] = (h16)kkn; ob[e8] = (h16)bn;
;                     owr[e8] = (h16)(dec * r); odec[e8] = (h16)dec; ok2[e8] = (h16)k2; ov[e8] = (h16)v;
	v_mov_b64_e32 v[168:169], v[248:249]
	v_mov_b64_e32 v[170:171], v[250:251]
	s_nop 0
	s_nop 1
	s_waitcnt vmcnt(8)
	v_mov_b64_e32 v[228:229], v[252:253]
	v_mov_b64_e32 v[230:231], v[254:255]
	global_load_dwordx4 v[232:235], v[152:153], off offset:16
	global_load_dwordx4 v[70:73], v[152:153], off offset:2064
	v_mov_b32_e32 v162, v172
	v_mul_f32_e32 v90, v86, v90
	v_mul_f32_e32 v25, 0x3fb8aa3b, v132
	v_fma_f32 v132, v32, v90, 0
	v_mov_b32_e32 v90, v173
	v_mul_f32_e32 v32, v87, v91
	v_pk_fma_f32 v[162:163], v[86:87], v[162:163], 0 op_sel_hi:[0,1,0]
	v_fmac_f32_e32 v132, v33, v32
	v_mov_b32_e32 v32, v176
	v_mov_b32_e32 v33, v88
	v_mul_f32_e32 v88, v82, v88
	v_pk_fma_f32 v[86:87], v[86:87], v[90:91], v[162:163] op_sel:[1,0,0]
	v_fmac_f32_e32 v132, v34, v88
	v_mov_b32_e32 v88, v177
	v_mul_f32_e32 v34, v83, v89
	v_pk_fma_f32 v[32:33], v[82:83], v[32:33], v[86:87] op_sel_hi:[0,1,1]
	v_exp_f32_e32 v24, v150
	v_fmac_f32_e32 v132, v35, v34
	v_mov_b32_e32 v34, v182
	v_mov_b32_e32 v35, v174
	v_mul_f32_e32 v150, v92, v174
	v_pk_fma_f32 v[32:33], v[82:83], v[88:89], v[32:33] op_sel:[1,0,0]
	v_fmac_f32_e32 v132, v46, v150
	v_mov_b32_e32 v174, v183
	v_mul_f32_e32 v46, v93, v175
	v_pk_fma_f32 v[32:33], v[92:93], v[34:35], v[32:33] op_sel_hi:[0,1,1]
	v_fmac_f32_e32 v132, v47, v46
	v_mov_b32_e32 v46, v196
	v_mov_b32_e32 v47, v180
	v_mul_f32_e32 v150, v84, v180
	v_pk_fma_f32 v[32:33], v[92:93], v[174:175], v[32:33] op_sel:[1,0,0]
	v_add_f32_e32 v29, v29, v75
	v_fmac_f32_e32 v132, v48, v150
	v_pk_fma_f32 v[32:33], v[84:85], v[46:47], v[32:33] op_sel_hi:[0,1,1]
	v_mov_b32_e32 v180, v197
	v_mul_f32_e32 v34, v85, v181
	v_mul_f32_e32 v29, 0xbfb8aa3b, v29
	v_fmac_f32_e32 v132, v49, v34
	v_pk_fma_f32 v[34:35], v[84:85], v[180:181], v[32:33] op_sel:[1,0,0]
	v_pk_mul_f32 v[32:33], v[178:179], v[130:131] op_sel_hi:[1,0]
	v_exp_f32_e32 v29, v29
	v_mov_b32_e32 v46, v32
	v_mov_b32_e32 v47, v192
	v_mov_b32_e32 v187, v193
	v_pk_mul_f32 v[82:83], v[46:47], v[186:187]
	v_add_f32_e32 v24, 1.0, v24
	v_exp_f32_e32 v74, v25
	v_add_f32_e32 v25, -1.0, v28
	v_rcp_f32_e32 v24, v24
	v_mov_b32_e32 v200, v33
	v_fma_f32 v155, v58, v25, 1.0
	v_add_f32_e32 v25, 1.0, v29
	v_pk_mul_f32 v[84:85], v[200:201], v[160:161]
	v_rcp_f32_e32 v58, v25
	v_mul_f32_e32 v24, 0xbf1b4598, v24
	v_mul_f32_e32 v24, 0x3fb8aa3b, v24
	v_exp_f32_e32 v75, v24
	v_add_f32_e32 v24, -1.0, v58
	v_fma_f32 v153, v59, v24, 1.0
	v_cvt_pk_f16_f32 v24, v78, v79
	v_cvt_pk_f16_f32 v32, v32, v33
	v_mul_f32_e32 v26, 0xbfb8aa3b, v26
	v_mul_f32_e32 v27, 0xbfb8aa3b, v27
	v_exp_f32_e32 v26, v26
	v_exp_f32_e32 v27, v27
	v_mov_b32_e32 v29, v164
	v_mov_b32_e32 v59, v165
	v_add_f32_e32 v26, 1.0, v26
	v_add_f32_e32 v25, 1.0, v27
	v_rcp_f32_e32 v26, v26
	v_rcp_f32_e32 v25, v25
	v_pk_fma_f32 v[22:23], v[22:23], v[44:45], s[0:1]
	v_pk_mov_b32 v[20:21], v[20:21], v[30:31] op_sel:[1,0]
	v_mul_f32_e32 v26, 0xbf1b4598, v26
	v_mul_f32_e32 v25, 0xbf1b4598, v25
	v_mov_b32_e32 v22, v151
	s_nop 0
	v_cndmask_b32_e64 v49, v168, 0, s[6:7]
	v_lshlrev_b32_e32 v48, 16, v49
	s_waitcnt vmcnt(1)
	v_lshlrev_b32_e32 v46, 16, v232
	v_and_b32_e32 v47, 0xffff0000, v232
	v_and_b32_e32 v49, 0xffff0000, v49
	v_pk_add_f32 v[48:49], v[48:49], v[46:47] neg_lo:[0,1] neg_hi:[0,1]
	v_cndmask_b32_e64 v89, v228, 0, s[6:7]
	v_pk_fma_f32 v[48:49], v[62:63], v[48:49], v[46:47]
	v_cndmask_b32_e64 v92, v169, 0, s[6:7]
	v_pk_mul_f32 v[46:47], v[48:49], v[82:83] op_sel_hi:[0,1]
	v_pk_fma_f32 v[34:35], v[48:49], v[82:83], v[34:35] op_sel_hi:[0,1,1]
	v_fmac_f32_e32 v132, v66, v47
	v_pk_mul_f32 v[62:63], v[48:49], v[84:85]
	v_pk_mul_f32 v[46:47], v[48:49], v[78:79]
	v_pk_fma_f32 v[34:35], v[48:49], v[84:85], v[34:35] op_sel:[1,0,0]
	v_fmac_f32_e32 v132, v67, v63
	s_waitcnt vmcnt(0)
; #define LAS __attribute__((address_space(3)))
; __device__ __forceinline__ float fast_sigmoid(float x) { return __builtin_amdgcn_rcpf(1.f + __expf(-x)); }
; __device__ __forceinline__ void prep_rwkv_phase(const Params& p, LAS unsigned char* lds, int gw, int ngw, int wave, int lane) {
;     ...
;         for (int hf = 0; hf < 2; ++hf) {
;             h16x8 owr, odec, ok2, ov, okk, ob;
;             const int o_ = h * 64 + fq * 16 + hf * 8;
;             const u32x4 rc = *(const u32x4*)(prow + o_), kc = kcs[hf], vc = *(const u32x4*)(prow + 1024 + o_);
;             u32x4 rp = *(const u32x4*)(pprev + o_), vp = *(const u32x4*)(pprev + 1024 + o_); const u32x4 kp = kps[hf];
;             if (first) { rp = (u32x4){0u, 0u, 0u, 0u}; vp = rp; }
; #pragma unroll
;             for (int i2 = 0; i2 < 2; ++i2) {
;                 const int i = 2 * hf + i2, c = h * 64 + i * 16 + 4 * fq;
;                 const f32x4 mur = *(const LAS f32x4*)(PRM + c), muk = *(const LAS f32x4*)(PRM + 512 + c), muv = *(const LAS f32x4*)(PRM + 1024 + c);
;                 const f32x4 w04 = *(const LAS f32x4*)(PRM + 1536 + c), a04 = *(const LAS f32x4*)(PRM + 2048 + c), kk4 = *(const LAS f32x4*)(PRM + 2560 + c), ka4 = *(const LAS f32x4*)(PRM + 3072 + c), rk4 = *(const LAS f32x4*)(PRM + 3584 + c);
; #pragma unroll
;                 for (int j = 0; j < 4; ++j) {
;                     const int e8 = i2 * 4 + j, e = hf * 8 + e8; const unsigned wsel = (e8 >> 1); const bool hiw = e8 & 1;
;     ...
;                     const float rcur = PREP_GET(rc), rprv = PREP_GET(rp), kcur = PREP_GET(kc), kprv = PREP_GET(kp), vcur = PREP_GET(vc), vprv = PREP_GET(vp);
;     ...
;                     const float r = rcur + (rprv - rcur) * mur[j], k = kcur + (kprv - kcur) * muk[j], v = vcur + (vprv - vcur) * muv[j];
;                     const float dec = __expf(-0.60653066f * fast_sigmoid(w04[j] + accD[i][j]));
;                     const float a = fast_sigmoid(a04[j] + accA[i][j]);
;                     const float kraw = k * kk4[j], k2 = k * (1.f + (a - 1.f) * ka4[j]);
;                     const float kkn = kraw * inv, bn = kkn * a; sbr += bn * r; skr += k2 * r; sbo += r * k2 * rk4[j];
;                     okk[e8] = (h16)kkn; ob[e8] = (h16)bn;
;                     owr[e8] = (h16)(dec * r); odec[e8] = (h16)dec; ok2[e8] = (h16)k2; ov[e8] = (h16)v;
;                 }
;             }
	v_lshlrev_b32_e32 v48, 16, v70
	v_and_b32_e32 v49, 0xffff0000, v70
	v_lshlrev_b32_e32 v62, 16, v89
	v_and_b32_e32 v63, 0xffff0000, v89
	v_pk_add_f32 v[62:63], v[62:63], v[48:49] neg_lo:[0,1] neg_hi:[0,1]
	v_lshlrev_b32_e32 v78, 16, v92
	v_pk_fma_f32 v[48:49], v[50:51], v[62:63], v[48:49]
	v_and_b32_e32 v79, 0xffff0000, v92
	v_cvt_pk_f16_f32 v50, v48, v49
	v_pk_mul_f32 v[48:49], v[158:159], v[130:131] op_sel_hi:[1,0]
	v_cndmask_b32_e64 v88, v229, 0, s[6:7]
	v_mov_b32_e32 v194, v48
	v_cvt_pk_f16_f32 v33, v48, v49
	v_mov_b32_e32 v166, v49
	v_lshlrev_b32_e32 v48, 16, v233
	v_and_b32_e32 v49, 0xffff0000, v233
	v_pk_add_f32 v[78:79], v[78:79], v[48:49] neg_lo:[0,1] neg_hi:[0,1]
	v_pk_mul_f32 v[62:63], v[194:195], v[184:185]
	v_pk_fma_f32 v[48:49], v[64:65], v[78:79], v[48:49]
	v_pk_mul_f32 v[66:67], v[166:167], v[190:191]
	v_pk_mul_f32 v[64:65], v[48:49], v[62:63] op_sel_hi:[0,1]
	v_fmac_f32_e32 v132, v68, v65
	v_pk_mul_f32 v[64:65], v[48:49], v[80:81]
	v_cvt_pk_f16_f32 v46, v46, v47
	v_pk_fma_f32 v[34:35], v[48:49], v[62:63], v[34:35] op_sel_hi:[0,1,1]
	v_cvt_pk_f16_f32 v47, v64, v65
	v_pk_mul_f32 v[64:65], v[48:49], v[66:67]
	v_pk_fma_f32 v[48:49], v[48:49], v[66:67], v[34:35] op_sel:[1,0,0]
	v_fmac_f32_e32 v132, v69, v65
	v_lshlrev_b32_e32 v34, 16, v71
	v_and_b32_e32 v35, 0xffff0000, v71
	v_lshlrev_b32_e32 v64, 16, v88
	v_and_b32_e32 v65, 0xffff0000, v88
	v_pk_add_f32 v[64:65], v[64:65], v[34:35] neg_lo:[0,1] neg_hi:[0,1]
	v_cndmask_b32_e64 v91, v170, 0, s[6:7]
	v_pk_fma_f32 v[34:35], v[52:53], v[64:65], v[34:35]
	v_lshlrev_b32_e32 v52, 16, v234
	v_cvt_pk_f16_f32 v51, v34, v35
	v_pk_mul_f32 v[34:35], v[156:157], v[130:131] op_sel_hi:[1,0]
	v_and_b32_e32 v53, 0xffff0000, v234
	v_lshlrev_b32_e32 v64, 16, v91
	v_and_b32_e32 v65, 0xffff0000, v91
	v_mov_b32_e32 v154, v34
	v_pk_add_f32 v[64:65], v[64:65], v[52:53] neg_lo:[0,1] neg_hi:[0,1]
	v_pk_mul_f32 v[28:29], v[154:155], v[28:29]
	v_mov_b32_e32 v152, v35
	s_waitcnt lgkmcnt(1)
	v_pk_fma_f32 v[40:41], v[64:65], v[40:41], v[52:53]
	v_pk_mul_f32 v[58:59], v[152:153], v[58:59]
	v_pk_mul_f32 v[52:53], v[40:41], v[28:29] op_sel_hi:[0,1]
	v_cndmask_b32_e64 v87, v230, 0, s[6:7]
	v_fmac_f32_e32 v132, v54, v53
	v_pk_mul_f32 v[52:53], v[40:41], v[58:59]
	v_lshlrev_b32_e32 v54, 16, v87
	v_fmac_f32_e32 v132, v55, v53
	v_lshlrev_b32_e32 v52, 16, v72
	v_and_b32_e32 v53, 0xffff0000, v72
	v_and_b32_e32 v55, 0xffff0000, v87
	v_pk_add_f32 v[54:55], v[54:55], v[52:53] neg_lo:[0,1] neg_hi:[0,1]
	v_mul_f32_e32 v26, 0x3fb8aa3b, v26
	s_waitcnt lgkmcnt(0)
	v_pk_fma_f32 v[36:37], v[54:55], v[36:37], v[52:53]
	v_mul_f32_e32 v25, 0x3fb8aa3b, v25
	v_cvt_pk_f16_f32 v52, v36, v37
	v_pk_mul_f32 v[36:37], v[60:61], v[130:131]
	v_cndmask_b32_e64 v90, v171, 0, s[6:7]
	v_mov_b32_e32 v37, v23
	v_mov_b32_e32 v23, v44
	v_pk_mul_f32 v[44:45], v[36:37], v[22:23]
	v_pk_mul_f32 v[22:23], v[198:199], v[130:131]
	v_pk_fma_f32 v[54:55], v[76:77], v[30:31], s[0:1]
	v_exp_f32_e32 v188, v26
	v_exp_f32_e32 v189, v25
	v_cvt_pk_f16_f32 v34, v34, v35
	v_mov_b32_e32 v23, v55
	v_cvt_pk_f16_f32 v35, v36, v22
	v_lshlrev_b32_e32 v36, 16, v235
	v_and_b32_e32 v37, 0xffff0000, v235
	v_lshlrev_b32_e32 v54, 16, v90
	v_and_b32_e32 v55, 0xffff0000, v90
	v_pk_add_f32 v[54:55], v[54:55], v[36:37] neg_lo:[0,1] neg_hi:[0,1]
	v_pk_fma_f32 v[64:65], v[40:41], v[28:29], v[48:49] op_sel_hi:[0,1,1]
	v_pk_fma_f32 v[36:37], v[54:55], v[42:43], v[36:37]
	v_pk_mul_f32 v[48:49], v[40:41], v[74:75]
	v_pk_mul_f32 v[42:43], v[36:37], v[44:45] op_sel_hi:[0,1]
	v_pk_fma_f32 v[40:41], v[40:41], v[58:59], v[64:65] op_sel:[1,0,0]
	v_pk_mul_f32 v[30:31], v[22:23], v[20:21]
	v_fmac_f32_e32 v132, v56, v43
	v_pk_mul_f32 v[42:43], v[36:37], v[188:189]
	v_cndmask_b32_e64 v86, v231, 0, s[6:7]
	v_cvt_pk_f16_f32 v48, v48, v49
	v_pk_fma_f32 v[40:41], v[36:37], v[44:45], v[40:41] op_sel_hi:[0,1,1]
	v_cvt_pk_f16_f32 v49, v42, v43
	v_pk_mul_f32 v[42:43], v[36:37], v[30:31]
	v_cvt_pk_f16_f32 v23, v44, v30
	v_cvt_pk_f16_f32 v22, v28, v58
	v_pk_fma_f32 v[36:37], v[36:37], v[30:31], v[40:41] op_sel:[1,0,0]
	v_fmac_f32_e32 v132, v57, v43
	v_cvt_pk_f16_f32 v43, v45, v31
	v_cvt_pk_f16_f32 v42, v29, v59
	v_lshlrev_b32_e32 v28, 16, v73
	v_and_b32_e32 v29, 0xffff0000, v73
	v_lshlrev_b32_e32 v30, 16, v86
	v_and_b32_e32 v31, 0xffff0000, v86
	v_pk_add_f32 v[30:31], v[30:31], v[28:29] neg_lo:[0,1] neg_hi:[0,1]
	v_cvt_pk_f16_f32 v21, v62, v66
	v_pk_fma_f32 v[28:29], v[30:31], v[38:39], v[28:29]
	ds_bpermute_b32 v30, v145, v36
	ds_bpermute_b32 v31, v145, v37
	v_cvt_pk_f16_f32 v53, v28, v29
	ds_bpermute_b32 v28, v145, v132
	v_cvt_pk_f16_f32 v20, v82, v84
	global_store_dwordx4 v[0:1], v[20:23], off offset:16
	v_cvt_pk_f16_f32 v27, v188, v189
	v_cvt_pk_f16_f32 v26, v74, v75
	s_waitcnt lgkmcnt(1)
	v_pk_add_f32 v[20:21], v[36:37], v[30:31]
	s_waitcnt lgkmcnt(0)
	v_add_f32_e32 v28, v132, v28
	ds_bpermute_b32 v22, v2, v20
	ds_bpermute_b32 v23, v2, v21
	ds_bpermute_b32 v2, v2, v28
	v_cvt_pk_f16_f32 v25, v80, v81
	v_cvt_pk_f16_f32 v41, v63, v67
	v_cvt_pk_f16_f32 v40, v83, v85
	global_store_dwordx4 v[0:1], v[32:35], off offset:-368
	global_store_dwordx4 v[0:1], v[46:49], off offset:-240
	global_store_dwordx4 v[0:1], v[24:27], off offset:-112
	global_store_dwordx4 v[0:1], v[40:43], off offset:144
	global_store_dwordx4 v[0:1], v[50:53], off offset:272
	s_and_saveexec_b64 s[8:9], s[4:5]
	s_cbranch_execz .LBB0_860
	v_lshl_add_u64 v[24:25], s[92:93], 0, v[138:139]
	s_waitcnt lgkmcnt(1)
	v_pk_add_f32 v[0:1], v[20:21], v[22:23]
	s_waitcnt lgkmcnt(0)
	v_add_f32_e32 v2, v28, v2
	global_store_dwordx4 v[24:25], v[0:3], off

; __global__ void __launch_bounds__(512, 2) mega_fwd(Params p) {
	.amdhsa_kernel _Z8mega_fwd6Params
		.amdhsa_group_segment_fixed_size 0
		.amdhsa_private_segment_fixed_size 0
		.amdhsa_kernarg_size 504
		.amdhsa_user_sgpr_count 2
		.amdhsa_user_sgpr_dispatch_ptr 0
		.amdhsa_user_sgpr_queue_ptr 0
		.amdhsa_user_sgpr_kernarg_segment_ptr 1
		.amdhsa_user_sgpr_dispatch_id 0
		.amdhsa_user_sgpr_kernarg_preload_length 0
		.amdhsa_user_sgpr_kernarg_preload_offset 0
		.amdhsa_user_sgpr_private_segment_size 0
		.amdhsa_uses_dynamic_stack 0
		.amdhsa_enable_private_segment 0
		.amdhsa_system_sgpr_workgroup_id_x 1
		.amdhsa_system_sgpr_workgroup_id_y 0
		.amdhsa_system_sgpr_workgroup_id_z 0
		.amdhsa_system_sgpr_workgroup_info 0
		.amdhsa_system_vgpr_workitem_id 2
		.amdhsa_next_free_vgpr 256
		.amdhsa_next_free_sgpr 102
		.amdhsa_accum_offset 256
		.amdhsa_reserve_vcc 1
		.amdhsa_float_round_mode_32 0
		.amdhsa_float_round_mode_16_64 0
		.amdhsa_float_denorm_mode_32 3
		.amdhsa_float_denorm_mode_16_64 3
		.amdhsa_dx10_clamp 1
		.amdhsa_ieee_mode 1
		.amdhsa_fp16_overflow 0
		.amdhsa_tg_split 0
		.amdhsa_exception_fp_ieee_invalid_op 0
		.amdhsa_exception_fp_denorm_src 0
		.amdhsa_exception_fp_ieee_div_zero 0
		.amdhsa_exception_fp_ieee_overflow 0
		.amdhsa_exception_fp_ieee_underflow 0
		.amdhsa_exception_fp_ieee_inexact 0
		.amdhsa_exception_int_div_zero 0
	.end_amdhsa_kernel

; __global__ void __launch_bounds__(512, 2) mega_fwd(Params p) {
amdhsa.kernels:
  - .agpr_count:     0
    .args:
      - .offset:         0
        .size:           248
        .value_kind:     by_value
      - .offset:         248
        .size:           4
        .value_kind:     hidden_block_count_x
      - .offset:         252
        .size:           4
        .value_kind:     hidden_block_count_y
      - .offset:         256
        .size:           4
        .value_kind:     hidden_block_count_z
      - .offset:         260
        .size:           2
        .value_kind:     hidden_group_size_x
      - .offset:         262
        .size:           2
        .value_kind:     hidden_group_size_y
      - .offset:         264
        .size:           2
        .value_kind:     hidden_group_size_z
      - .offset:         266
        .size:           2
        .value_kind:     hidden_remainder_x
      - .offset:         268
        .size:           2
        .value_kind:     hidden_remainder_y
      - .offset:         270
        .size:           2
        .value_kind:     hidden_remainder_z
      - .offset:         288
        .size:           8
        .value_kind:     hidden_global_offset_x
      - .offset:         296
        .size:           8
        .value_kind:     hidden_global_offset_y
      - .offset:         304
        .size:           8
        .value_kind:     hidden_global_offset_z
      - .offset:         312
        .size:           2
        .value_kind:     hidden_grid_dims
      - .offset:         336
        .size:           8
        .value_kind:     hidden_multigrid_sync_arg
      - .offset:         368
        .size:           4
        .value_kind:     hidden_dynamic_lds_size
    .group_segment_fixed_size: 0
    .kernarg_segment_align: 8
    .kernarg_segment_size: 504
    .language:       OpenCL C
    .language_version:
      - 2
      - 0
    .max_flat_workgroup_size: 512
    .name:           _Z8mega_fwd6Params
    .private_segment_fixed_size: 0
    .sgpr_count:     108
    .sgpr_spill_count: 61
    .symbol:         _Z8mega_fwd6Params.kd
    .uniform_work_group_size: 1
    .uses_dynamic_stack: false
    .vgpr_count:     256
    .vgpr_spill_count: 0
    .wavefront_size: 64
